# c4 minus the compiler-inserted vmcnt(0) at the P1 tile-loop header (epilogue store drain overlaps first K-step)
# baseline (speedup 1.0000x reference)
.LBB0_317:
	s_ashr_i32 s27, s26, 31
	s_lshl_b64 s[28:29], s[26:27], 20
	s_add_u32 s28, s42, s28
	s_addc_u32 s29, s43, s29
	s_and_b64 s[30:31], s[4:5], exec
	s_cselect_b32 s9, s29, s7
	s_cselect_b32 s27, s28, s6
	s_ashr_i32 s25, s24, 31
	s_lshl_b64 s[30:31], s[24:25], 20
	s_add_u32 s30, s44, s30
	s_addc_u32 s31, s45, s31
	s_and_b64 s[38:39], s[4:5], exec
	s_cselect_b32 s25, s31, s37
	s_cselect_b32 s62, s30, s36
	s_ashr_i32 s35, s34, 31
	s_lshl_b64 s[38:39], s[34:35], 13
	s_add_u32 s35, s36, 0x100
	v_mov_b32_e32 v0, 0
	v_mov_b32_e32 v179, v178
	v_mov_b32_e32 v178, v191
	v_mov_b32_e32 v191, v190
	v_mov_b32_e32 v190, v185
	v_mov_b32_e32 v185, v215
	v_mov_b32_e32 v203, v214
	v_lshl_add_u64 v[128:129], v[164:165], 0, s[38:39]
	v_lshl_add_u64 v[130:131], s[6:7], 0, v[170:171]
	v_lshl_add_u64 v[132:133], s[6:7], 0, v[172:173]
	s_addc_u32 s63, s37, 0
	s_mov_b32 s64, -2
	s_mov_b64 s[36:37], 0
	v_mov_b32_e32 v1, v0
	v_mov_b32_e32 v2, v0
	v_mov_b32_e32 v3, v0
	v_mov_b32_e32 v4, v0
	v_mov_b32_e32 v5, v0
	v_mov_b32_e32 v6, v0
	v_mov_b32_e32 v7, v0
	v_mov_b32_e32 v8, v0
	v_mov_b32_e32 v9, v0
	v_mov_b32_e32 v10, v0
	v_mov_b32_e32 v11, v0
	v_mov_b32_e32 v12, v0
	v_mov_b32_e32 v13, v0
	v_mov_b32_e32 v14, v0
	v_mov_b32_e32 v15, v0
	v_mov_b32_e32 v20, v0
	v_mov_b32_e32 v21, v0
	v_mov_b32_e32 v22, v0
	v_mov_b32_e32 v23, v0
	v_mov_b32_e32 v24, v0
	v_mov_b32_e32 v25, v0
	v_mov_b32_e32 v26, v0
	v_mov_b32_e32 v27, v0
	v_mov_b32_e32 v36, v0
	v_mov_b32_e32 v37, v0
	v_mov_b32_e32 v38, v0
	v_mov_b32_e32 v39, v0
	v_mov_b32_e32 v40, v0
	v_mov_b32_e32 v41, v0
	v_mov_b32_e32 v42, v0
	v_mov_b32_e32 v43, v0
	v_mov_b32_e32 v112, v0
	v_mov_b32_e32 v113, v0
	v_mov_b32_e32 v114, v0
	v_mov_b32_e32 v115, v0
	v_mov_b32_e32 v116, v0
	v_mov_b32_e32 v117, v0
	v_mov_b32_e32 v118, v0
	v_mov_b32_e32 v119, v0
	v_mov_b32_e32 v16, v0
	v_mov_b32_e32 v17, v0
	v_mov_b32_e32 v18, v0
	v_mov_b32_e32 v19, v0
	v_mov_b32_e32 v28, v0
	v_mov_b32_e32 v29, v0
	v_mov_b32_e32 v30, v0
	v_mov_b32_e32 v31, v0
	v_mov_b32_e32 v32, v0
	v_mov_b32_e32 v33, v0
	v_mov_b32_e32 v34, v0
	v_mov_b32_e32 v35, v0
	v_mov_b32_e32 v44, v0
	v_mov_b32_e32 v45, v0
	v_mov_b32_e32 v46, v0
	v_mov_b32_e32 v47, v0
	v_mov_b32_e32 v48, v0
	v_mov_b32_e32 v49, v0
	v_mov_b32_e32 v50, v0
	v_mov_b32_e32 v51, v0
	v_mov_b32_e32 v52, v0
	v_mov_b32_e32 v53, v0
	v_mov_b32_e32 v54, v0
	v_mov_b32_e32 v55, v0
	v_mov_b32_e32 v56, v0
	v_mov_b32_e32 v57, v0
	v_mov_b32_e32 v58, v0
	v_mov_b32_e32 v59, v0
	v_mov_b32_e32 v60, v0
	v_mov_b32_e32 v61, v0
	v_mov_b32_e32 v62, v0
	v_mov_b32_e32 v63, v0
	v_mov_b32_e32 v68, v0
	v_mov_b32_e32 v69, v0
	v_mov_b32_e32 v70, v0
	v_mov_b32_e32 v71, v0
	v_mov_b32_e32 v72, v0
	v_mov_b32_e32 v73, v0
	v_mov_b32_e32 v74, v0
	v_mov_b32_e32 v75, v0
	v_mov_b32_e32 v84, v0
	v_mov_b32_e32 v85, v0
	v_mov_b32_e32 v86, v0
	v_mov_b32_e32 v87, v0
	v_mov_b32_e32 v88, v0
	v_mov_b32_e32 v89, v0
	v_mov_b32_e32 v90, v0
	v_mov_b32_e32 v91, v0
	v_mov_b32_e32 v100, v0
	v_mov_b32_e32 v101, v0
	v_mov_b32_e32 v102, v0
	v_mov_b32_e32 v103, v0
	v_mov_b32_e32 v104, v0
	v_mov_b32_e32 v105, v0
	v_mov_b32_e32 v106, v0
	v_mov_b32_e32 v107, v0
	v_mov_b32_e32 v64, v0
	v_mov_b32_e32 v65, v0
	v_mov_b32_e32 v66, v0
	v_mov_b32_e32 v67, v0
	v_mov_b32_e32 v76, v0
	v_mov_b32_e32 v77, v0
	v_mov_b32_e32 v78, v0
	v_mov_b32_e32 v79, v0
	v_mov_b32_e32 v80, v0
	v_mov_b32_e32 v81, v0
	v_mov_b32_e32 v82, v0
	v_mov_b32_e32 v83, v0
	v_mov_b32_e32 v92, v0
	v_mov_b32_e32 v93, v0
	v_mov_b32_e32 v94, v0
	v_mov_b32_e32 v95, v0
	v_mov_b32_e32 v96, v0
	v_mov_b32_e32 v97, v0
	v_mov_b32_e32 v98, v0
	v_mov_b32_e32 v99, v0
	v_mov_b32_e32 v108, v0
	v_mov_b32_e32 v109, v0
	v_mov_b32_e32 v110, v0
	v_mov_b32_e32 v111, v0
	v_mov_b32_e32 v120, v0
	v_mov_b32_e32 v121, v0
	v_mov_b32_e32 v122, v0
	v_mov_b32_e32 v123, v0
	v_mov_b32_e32 v124, v0
	v_mov_b32_e32 v125, v0
	v_mov_b32_e32 v126, v0
	v_mov_b32_e32 v127, v0
	s_branch .LBB0_319
